# conv tile pairs 256..287 moved from the P2 phase (last 32 workgroups were its critical path) to segment 6 of the HGRN2 pass-2 phase
# speedup vs baseline: 1.0713x; 1.0147x over previous
; template <int TT>
; __device__ __forceinline__ void conv_pair(const Params& p, unsigned char* lds, bool sample, int tile) {
;     int tid = threadIdx.x; asm volatile("" : "+v"(tid));
;     const int half = tid >> 8, cp = tid & 255, lane = tid & 63, wq = (tid >> 6) & 3;
;     unsigned char* ws = p.ws; const bf16_t* U = (const bf16_t*)(ws + WS_U); bf16_t* CAT = (bf16_t*)(ws + WS_CAT);
;     const int sq = sample ? tile : tile >> 7, t0 = sample ? 0 : (tile & 127) * 16;
;     const int row0 = sample ? MP + sq * DS : sq * SEQ + t0;
;     float* zb = (float*)lds + (size_t)half * (TT * MIXB);
; __global__ void __launch_bounds__(512, 2) hymba_fwd(Params p) {
;     ...
;         for (int u = CONV_MOVED + bx; u < NB * (SEQ / 16) / 2; u += G) conv_pair<16>(p, lds, false, 2 * u + (threadIdx.x >> 8));
.Lp2_conv:
	s_cmpk_lt_i32 s2, 0x100
	s_cselect_b64 s[28:29], -1, 0
	s_cmpk_gt_i32 s2, 0xdf
	s_cbranch_scc1 .LBB0_400
	v_lshl_add_u32 v0, s2, 1, v96
	v_add_u32_e32 v89, 0x240, v0
	v_lshlrev_b32_e32 v0, 4, v96
	v_lshl_add_u32 v0, s2, 5, v0
	s_add_i32 s1, s2, 0x120
	s_lshl_b32 s3, s66, 1
	v_add_u32_e32 v90, 0x2403, v0
	s_lshl_b32 s10, s66, 5
	v_mov_b32_e32 v17, 0
	v_mov_b32_e32 v91, 0x358637bd
	s_mov_b32 s11, 0x800000
	s_mov_b32 s12, 0x96f6000
	s_branch .LBB0_336

; __global__ void __launch_bounds__(512, 2) hymba_fwd(Params p) {
;     ...
;         for (int u = bx; u < NB * HEADS * NSEG; u += G) { hgrn_seg<true>(p, lds, u >> 5, (u >> 3) & 3, u & 7);
;             const int seg = u & 7, ne = seg < 2 ? 2 : (seg < 6 ? 1 : 0), o0 = (int)((0x88765420u >> (4 * seg)) & 15u);
;             for (int k = 0; k < ne; ++k) conv_pair<16>(p, lds, false, 2 * ((u >> 3) * 8 + o0 + k) + (threadIdx.x >> 8)); }
.LBB0_482:
	s_cmp_lt_u32 s49, 7
	s_cselect_b64 s[46:47], -1, 0
	v_cndmask_b32_e64 v0, 0, 1, s[46:47]
	s_waitcnt lgkmcnt(0)
	s_barrier
	s_cmp_gt_u32 s49, 1
	v_readfirstlane_b32 s4, v0
	s_cselect_b32 s4, s4, 2
	v_readlane_b32 s64, v247, 38
	v_readlane_b32 s52, v247, 36
	s_cmp_eq_u32 s4, 0
	v_readlane_b32 s65, v247, 39
	v_readlane_b32 s66, v247, 40
	v_readlane_b32 s67, v247, 41
	v_readlane_b32 s53, v247, 37
	s_cbranch_scc1 .LBB0_461
	s_lshl_b32 s46, s48, 4
	s_lshl_b32 s47, s48, 8
	s_cmp_eq_u32 s49, 6
	s_cbranch_scc1 .Lp2b_seg6
	s_lshl_b32 s48, s49, 2
	s_lshr_b32 s48, 0x88765420, s48
	s_and_b32 s49, s48, 15
	s_lshl_b32 s48, s4, 5
	s_lshl_b32 s4, s49, 1
	s_add_i32 s4, s4, s46
	v_add_u32_e32 v136, s4, v96
	s_lshl_b32 s4, s49, 5
	s_add_i32 s4, s4, s47
	v_add_u32_e32 v137, s4, v130
	s_mov_b32 s49, 0
	s_branch .LBB0_485
.Lp2b_seg6:
	s_lshr_b32 s46, s46, 3
	s_addk_i32 s46, 0x200
	v_add_u32_e32 v136, s46, v96
	s_lshr_b32 s47, s47, 3
	s_addk_i32 s47, 0x2000
	v_add_u32_e32 v137, s47, v130
	s_lshl_b32 s48, s4, 5
	s_mov_b32 s49, 0
	s_branch .LBB0_485
